# plus attention P.V: the four V reads feeding the first MFMA group issued first
# speedup vs baseline: 1.0026x; 1.0026x over previous
.LBB0_963:
	s_add_u32 s36, s28, s30
	s_addc_u32 s37, s29, s31
	s_add_u32 s34, s36, 0x100000
	s_addc_u32 s35, s37, 0
	s_lshl_b32 s9, s19, 14
	s_add_i32 s48, s95, s9
	s_mov_b32 m0, s48
	s_nop 0
	global_load_lds_dwordx4 v228, s[34:35]
	s_add_i32 m0, s48, 0x400
	s_nop 0
	global_load_lds_dwordx4 v231, s[34:35]
	ds_read_b128 v[236:239], v196 offset:12288
	s_waitcnt lgkmcnt(3)
	v_mfma_f32_16x16x32_bf16 v[120:123], v[184:187], v[36:39], v[120:123]
	v_exp_f32_e32 v196, v132
	v_exp_f32_e32 v208, v133
	v_add_f32_e32 v206, v152, v206
	v_add_f32_e32 v207, v136, v207
	v_mfma_f32_16x16x32_bf16 v[124:127], v[184:187], v[0:3], v[124:127]
	v_add_u32_e32 v209, s25, v233
	ds_read_b128 v[184:187], v209
	v_exp_f32_e32 v210, v134
	v_exp_f32_e32 v211, v135
	s_waitcnt lgkmcnt(3)
	v_mfma_f32_16x16x32_bf16 v[132:135], v[176:179], v[0:3], v[148:151]
	v_mfma_f32_16x16x32_bf16 v[160:163], v[176:179], v[36:39], v[160:163]
	s_nop 1
	v_add_f32_e32 v148, v153, v206
	v_add_f32_e32 v149, v137, v207
	ds_read_b128 v[176:179], v209 offset:4096
	s_waitcnt lgkmcnt(3)
	v_mfma_f32_16x16x32_bf16 v[164:167], v[180:183], v[0:3], v[164:167]
	v_exp_f32_e32 v212, v128
	v_exp_f32_e32 v213, v129
	v_add_f32_e32 v148, v154, v148
	v_mfma_f32_16x16x32_bf16 v[168:171], v[180:183], v[36:39], v[168:171]
	v_add_f32_e32 v149, v138, v149
	ds_read_b128 v[180:183], v209 offset:8192
	v_exp_f32_e32 v219, v130
	v_exp_f32_e32 v235, v131
	s_waitcnt lgkmcnt(3)
	v_mfma_f32_16x16x32_bf16 v[128:131], v[236:239], v[0:3], v[140:143]
	v_add_f32_e32 v148, v155, v148
	v_add_f32_e32 v149, v139, v149
	v_mfma_f32_16x16x32_bf16 v[140:143], v[236:239], v[36:39], v[172:175]
	s_nop 2
	ds_read_b128 v[172:175], v209 offset:12288
	s_waitcnt lgkmcnt(3)
	v_mfma_f32_16x16x32_bf16 v[120:123], v[184:187], v[28:31], v[120:123]
	v_add_f32_e32 v150, v188, v148
	v_add_f32_e32 v149, v190, v149
	v_mfma_f32_16x16x32_bf16 v[124:127], v[184:187], v[12:15], v[124:127]
	v_cvt_pk_bf16_f32 v148, v156, v157
	v_add_u32_e32 v206, s25, v230
	ds_read_b128 v[184:187], v206
	v_add_f32_e32 v150, v189, v150
	v_add_f32_e32 v151, v191, v149
	s_waitcnt lgkmcnt(3)
	v_mfma_f32_16x16x32_bf16 v[132:135], v[176:179], v[12:15], v[132:135]
	v_cvt_pk_bf16_f32 v149, v158, v159
	v_mfma_f32_16x16x32_bf16 v[156:159], v[176:179], v[28:31], v[160:163]
	ds_read_b128 v[176:179], v206 offset:4096
	s_waitcnt lgkmcnt(3)
	v_mfma_f32_16x16x32_bf16 v[162:165], v[180:183], v[12:15], v[164:167]
	s_nop 0
	v_add_f32_e32 v160, v194, v150
	v_add_f32_e32 v151, v192, v151
	v_mfma_f32_16x16x32_bf16 v[166:169], v[180:183], v[28:31], v[168:171]
	v_cvt_pk_bf16_f32 v150, v152, v153
	ds_read_b128 v[180:183], v206 offset:8192
	s_waitcnt lgkmcnt(3)
	v_mfma_f32_16x16x32_bf16 v[128:131], v[172:175], v[12:15], v[128:131]
	v_add_f32_e32 v160, v195, v160
	v_add_f32_e32 v161, v193, v151
	v_mfma_f32_16x16x32_bf16 v[140:143], v[172:175], v[28:31], v[140:143]
	v_cvt_pk_bf16_f32 v151, v154, v155
	ds_read_b128 v[152:155], v206 offset:12288
	s_waitcnt lgkmcnt(3)
	v_mfma_f32_16x16x32_bf16 v[120:123], v[184:187], v[24:27], v[120:123]
	v_add_f32_e32 v174, v196, v160
	v_add_f32_e32 v161, v212, v161
	v_mfma_f32_16x16x32_bf16 v[124:127], v[184:187], v[8:11], v[124:127]
	v_cvt_pk_bf16_f32 v160, v144, v145
	v_add_u32_e32 v186, s25, v226
	ds_read_b128 v[170:173], v186 offset:16384
	v_add_f32_e32 v184, v208, v174
	v_add_f32_e32 v185, v213, v161
	s_waitcnt lgkmcnt(3)
	v_mfma_f32_16x16x32_bf16 v[132:135], v[176:179], v[8:11], v[132:135]
	v_cvt_pk_bf16_f32 v161, v146, v147
	v_mfma_f32_16x16x32_bf16 v[144:147], v[176:179], v[24:27], v[156:159]
	s_nop 2
	ds_read_b128 v[156:159], v186 offset:18432
	s_waitcnt lgkmcnt(3)
	v_mfma_f32_16x16x32_bf16 v[174:177], v[180:183], v[8:11], v[162:165]
	v_mfma_f32_16x16x32_bf16 v[178:181], v[180:183], v[24:27], v[166:169]
	s_nop 1
	v_add_f32_e32 v163, v210, v184
	v_add_f32_e32 v164, v219, v185
	v_cvt_pk_bf16_f32 v162, v136, v137
	ds_read_b128 v[182:185], v186 offset:20480
	v_add_f32_e32 v206, v211, v163
	v_add_f32_e32 v207, v235, v164
	s_waitcnt lgkmcnt(3)
	v_mfma_f32_16x16x32_bf16 v[128:131], v[152:155], v[8:11], v[128:131]
	v_cvt_pk_bf16_f32 v163, v138, v139
	v_mfma_f32_16x16x32_bf16 v[136:139], v[152:155], v[24:27], v[140:143]
	s_nop 2
	ds_read_b128 v[140:143], v186 offset:22528
	s_waitcnt lgkmcnt(3)
	v_mfma_f32_16x16x32_bf16 v[120:123], v[170:173], v[32:35], v[120:123]
	v_cvt_pk_bf16_f32 v164, v188, v189
	v_mfma_f32_16x16x32_bf16 v[124:127], v[170:173], v[16:19], v[124:127]
	v_add_u32_e32 v152, s25, v224
	ds_read_b128 v[168:171], v152 offset:16384
	s_waitcnt lgkmcnt(3)
	v_mfma_f32_16x16x32_bf16 v[132:135], v[156:159], v[16:19], v[132:135]
	v_cvt_pk_bf16_f32 v165, v194, v195
	v_mfma_f32_16x16x32_bf16 v[186:189], v[156:159], v[32:35], v[144:147]
	ds_read_b128 v[236:239], v152 offset:18432
	s_waitcnt lgkmcnt(3)
	v_mfma_f32_16x16x32_bf16 v[240:243], v[182:185], v[16:19], v[174:177]
	v_cvt_pk_bf16_f32 v166, v196, v208
	v_mfma_f32_16x16x32_bf16 v[176:179], v[182:185], v[32:35], v[178:181]
	s_nop 2
	ds_read_b128 v[180:183], v152 offset:20480
	s_waitcnt lgkmcnt(3)
	v_mfma_f32_16x16x32_bf16 v[128:131], v[140:143], v[16:19], v[128:131]
	v_cvt_pk_bf16_f32 v167, v210, v211
	v_mfma_f32_16x16x32_bf16 v[244:247], v[140:143], v[32:35], v[136:139]
	ds_read_b128 v[248:251], v152 offset:22528
	s_waitcnt lgkmcnt(3)
	v_mfma_f32_16x16x32_bf16 v[152:155], v[168:171], v[20:23], v[124:127]
	v_mfma_f32_16x16x32_bf16 v[144:147], v[168:171], v[44:47], v[120:123]
	v_cvt_pk_bf16_f32 v168, v190, v191
	s_waitcnt lgkmcnt(2)
	v_mfma_f32_16x16x32_bf16 v[156:159], v[236:239], v[20:23], v[132:135]
	v_cvt_pk_bf16_f32 v169, v192, v193
	v_mfma_f32_16x16x32_bf16 v[172:175], v[236:239], v[44:47], v[186:189]
	s_waitcnt lgkmcnt(1)
	v_mfma_f32_16x16x32_bf16 v[140:143], v[180:183], v[20:23], v[240:243]
	v_cvt_pk_bf16_f32 v170, v212, v213
	v_mfma_f32_16x16x32_bf16 v[136:139], v[180:183], v[44:47], v[176:179]
	s_waitcnt lgkmcnt(0)
	v_mfma_f32_16x16x32_bf16 v[132:135], v[248:251], v[20:23], v[128:131]
	v_cvt_pk_bf16_f32 v171, v219, v235
	v_mfma_f32_16x16x32_bf16 v[128:131], v[248:251], v[44:47], v[244:247]
	s_lshl_b32 s34, s8, 14
	s_add_i32 s48, s34, 0
	s_add_i32 s48, s48, 0x12000
	v_add_u32_e32 v196, s48, v222
	v_add_u32_e32 v219, s48, v223
	ds_read_b64_tr_b16 v[176:177], v219
	ds_read_b64_tr_b16 v[178:179], v219 offset:4096
	ds_read_b64_tr_b16 v[184:185], v219 offset:8192
	ds_read_b64_tr_b16 v[186:187], v219 offset:12288
	ds_read_b64_tr_b16 v[120:121], v196
	ds_read_b64_tr_b16 v[122:123], v196 offset:4096
	ds_read_b64_tr_b16 v[124:125], v196 offset:8192
	ds_read_b64_tr_b16 v[126:127], v196 offset:12288
	ds_read_b64_tr_b16 v[182:183], v219 offset:4608
	ds_read_b64_tr_b16 v[180:181], v219 offset:512
	ds_read_b64_tr_b16 v[190:191], v219 offset:12800
	ds_read_b64_tr_b16 v[188:189], v219 offset:8704
	s_waitcnt lgkmcnt(10)
	v_mfma_f32_16x16x32_bf16 v[112:115], v[176:179], v[148:151], v[112:115]
	v_mfma_f32_16x16x32_bf16 v[116:119], v[176:179], v[160:163], v[116:119]
	v_max_f32_e32 v176, v152, v153
	s_waitcnt lgkmcnt(8)
	v_mfma_f32_16x16x32_bf16 v[112:115], v[184:187], v[164:167], v[112:115]
	v_max3_f32 v176, v176, v154, v155
	v_max3_f32 v176, v176, v156, v157
	v_max3_f32 v208, v176, v158, v159
	v_mfma_f32_16x16x32_bf16 v[116:119], v[184:187], v[168:171], v[116:119]
	ds_read_b64_tr_b16 v[192:193], v196 offset:512
	ds_read_b64_tr_b16 v[194:195], v196 offset:4608
	ds_read_b64_tr_b16 v[236:237], v196 offset:8704
	ds_read_b64_tr_b16 v[238:239], v196 offset:12800
	s_waitcnt lgkmcnt(10)
	v_mfma_f32_16x16x32_bf16 v[108:111], v[120:123], v[148:151], v[108:111]
	v_mfma_f32_16x16x32_bf16 v[176:179], v[120:123], v[160:163], v[104:107]
	s_waitcnt lgkmcnt(8)
	v_mfma_f32_16x16x32_bf16 v[104:107], v[124:127], v[164:167], v[108:111]
	s_nop 5
	v_max3_f32 v108, v208, v140, v141
	v_max3_f32 v108, v108, v142, v143
	v_max3_f32 v108, v108, v132, v133
	v_max3_f32 v120, v108, v134, v135
	v_mfma_f32_16x16x32_bf16 v[108:111], v[124:127], v[168:171], v[176:179]
	ds_read_b64_tr_b16 v[184:185], v219 offset:1024
	ds_read_b64_tr_b16 v[186:187], v219 offset:5120
	s_nop 0
	ds_read_b64_tr_b16 v[176:177], v219 offset:9216
	ds_read_b64_tr_b16 v[178:179], v219 offset:13312
	s_waitcnt lgkmcnt(10)
	v_mfma_f32_16x16x32_bf16 v[96:99], v[180:183], v[148:151], v[96:99]
	v_max_f32_e32 v121, v144, v145
	s_waitcnt lgkmcnt(8)
	v_mfma_f32_16x16x32_bf16 v[96:99], v[188:191], v[164:167], v[96:99]
	v_max3_f32 v121, v121, v146, v147
	v_max3_f32 v121, v121, v172, v173
	v_max3_f32 v121, v121, v174, v175
	v_mfma_f32_16x16x32_bf16 v[100:103], v[180:183], v[160:163], v[100:103]
	v_mfma_f32_16x16x32_bf16 v[100:103], v[188:191], v[168:171], v[100:103]
	ds_read_b64_tr_b16 v[188:189], v196 offset:1024
	ds_read_b64_tr_b16 v[190:191], v196 offset:5120
	ds_read_b64_tr_b16 v[180:181], v196 offset:9216
	ds_read_b64_tr_b16 v[182:183], v196 offset:13312
	s_waitcnt lgkmcnt(10)
	v_mfma_f32_16x16x32_bf16 v[92:95], v[192:195], v[148:151], v[92:95]
	v_mfma_f32_16x16x32_bf16 v[122:125], v[192:195], v[160:163], v[88:91]
	s_waitcnt lgkmcnt(8)
	v_mfma_f32_16x16x32_bf16 v[88:91], v[236:239], v[164:167], v[92:95]
	s_nop 5
	v_max3_f32 v92, v121, v136, v137
	v_max3_f32 v92, v92, v138, v139
	v_max3_f32 v92, v92, v128, v129
	v_max3_f32 v121, v92, v130, v131
	v_mfma_f32_16x16x32_bf16 v[92:95], v[236:239], v[168:171], v[122:125]
	s_nop 2
	v_max_f32_e32 v122, v120, v121
	v_cmp_ge_f32_e32 vcc, s62, v122
	s_cmp_lg_u64 vcc, exec
	s_cselect_b64 s[34:35], -1, 0
	s_cmp_eq_u64 vcc, exec
	s_cbranch_scc1 .LBB0_965
	ds_bpermute_b32 v48, v220, v120
	v_max_f32_e32 v49, v120, v120
	v_max_f32_e32 v50, v121, v121
	s_waitcnt lgkmcnt(0)
	v_max_f32_e32 v48, v48, v48
	v_max_f32_e32 v48, v49, v48
	ds_bpermute_b32 v49, v221, v48
	s_waitcnt lgkmcnt(0)
	v_max3_f32 v48, v48, v49, 0
	ds_bpermute_b32 v49, v220, v121
	v_exp_f32_e64 v208, -v48
	v_sub_f32_e32 v152, v152, v48
	v_sub_f32_e32 v153, v153, v48
	v_sub_f32_e32 v154, v154, v48
	s_waitcnt lgkmcnt(0)
	v_max_f32_e32 v49, v49, v49
	v_max_f32_e32 v49, v50, v49
	ds_bpermute_b32 v50, v221, v49
	v_sub_f32_e32 v155, v155, v48
	v_sub_f32_e32 v156, v156, v48
	v_sub_f32_e32 v157, v157, v48
	v_sub_f32_e32 v158, v158, v48
	s_waitcnt lgkmcnt(0)
	v_max3_f32 v49, v49, v50, 0
	v_exp_f32_e64 v209, -v49
	v_pk_add_f32 v[202:203], v[202:203], v[48:49]
	v_sub_f32_e32 v159, v159, v48
	v_pk_add_f32 v[120:121], v[202:203], 0 neg_lo:[1,1] neg_hi:[1,1]
	v_xor_b32_e32 v124, 0x80000000, v203
	v_sub_f32_e32 v143, v143, v48
	v_sub_f32_e32 v142, v142, v48
	v_sub_f32_e32 v141, v141, v48
	v_sub_f32_e32 v140, v140, v48
	v_sub_f32_e32 v135, v135, v48
	v_sub_f32_e32 v134, v134, v48
	v_sub_f32_e32 v133, v133, v48
	v_sub_f32_e32 v132, v132, v48
	v_mov_b32_e32 v121, v120
	v_mov_b32_e32 v122, v120
	v_mov_b32_e32 v123, v120
	v_sub_f32_e32 v144, v144, v49
	v_sub_f32_e32 v145, v145, v49
	v_sub_f32_e32 v146, v146, v49
	v_sub_f32_e32 v147, v147, v49
	v_sub_f32_e32 v172, v172, v49
	v_sub_f32_e32 v173, v173, v49
	v_sub_f32_e32 v174, v174, v49
	v_sub_f32_e32 v175, v175, v49
	v_sub_f32_e32 v139, v139, v49
	v_sub_f32_e32 v138, v138, v49
	v_sub_f32_e32 v137, v137, v49
	v_sub_f32_e32 v136, v136, v49
	v_sub_f32_e32 v131, v131, v49
	v_sub_f32_e32 v130, v130, v49
	v_sub_f32_e32 v129, v129, v49
	v_sub_f32_e32 v128, v128, v49
	v_mov_b32_e32 v125, v124
	v_mov_b32_e32 v126, v124
	v_mov_b32_e32 v127, v124
	v_mov_b32_e32 v48, v120
	v_mov_b32_e32 v49, v120
	v_mov_b32_e32 v50, v120
	v_mov_b32_e32 v51, v120
	v_mov_b32_e32 v52, v124
	v_mov_b32_e32 v53, v124
	v_mov_b32_e32 v54, v124
	v_mov_b32_e32 v55, v124
	s_branch .LBB0_966

.LBB0_971:
	s_add_u32 s36, s36, 0x180000
	s_addc_u32 s37, s37, 0
	s_add_i32 s25, s48, s77
	s_mov_b32 m0, s25
	s_nop 0
	global_load_lds_dwordx4 v228, s[36:37]
	s_add_i32 m0, s25, 0x400
	s_nop 0
	global_load_lds_dwordx4 v231, s[36:37]
	ds_read_b128 v[246:249], v243 offset:12288
	s_waitcnt lgkmcnt(3)
	v_mfma_f32_16x16x32_bf16 v[164:167], v[192:195], v[0:3], v[164:167]
	v_exp_f32_e32 v210, v132
	v_exp_f32_e32 v211, v133
	v_add_f32_e32 v212, v156, v245
	v_mfma_f32_16x16x32_bf16 v[160:163], v[192:195], v[36:39], v[160:163]
	v_add_f32_e32 v213, v148, v244
	v_add_u32_e32 v243, s49, v233
	ds_read_b128 v[192:195], v243
	v_exp_f32_e32 v250, v134
	v_exp_f32_e32 v251, v135
	s_waitcnt lgkmcnt(3)
	v_mfma_f32_16x16x32_bf16 v[132:135], v[188:191], v[0:3], v[180:183]
	v_add_f32_e32 v212, v157, v212
	v_add_f32_e32 v213, v149, v213
	v_mfma_f32_16x16x32_bf16 v[172:175], v[188:191], v[36:39], v[172:175]
	ds_read_b128 v[180:183], v243 offset:4096
	s_waitcnt lgkmcnt(3)
	v_mfma_f32_16x16x32_bf16 v[176:179], v[184:187], v[0:3], v[176:179]
	v_exp_f32_e32 v215, v128
	v_exp_f32_e32 v214, v129
	v_add_f32_e32 v188, v158, v212
	v_mfma_f32_16x16x32_bf16 v[140:143], v[184:187], v[36:39], v[140:143]
	v_add_f32_e32 v189, v150, v213
	ds_read_b128 v[184:187], v243 offset:8192
	v_exp_f32_e32 v218, v130
	v_exp_f32_e32 v198, v131
	s_waitcnt lgkmcnt(3)
	v_mfma_f32_16x16x32_bf16 v[128:131], v[246:249], v[0:3], v[168:171]
	v_add_f32_e32 v199, v159, v188
	v_add_f32_e32 v212, v151, v189
	v_mfma_f32_16x16x32_bf16 v[168:171], v[246:249], v[36:39], v[136:139]
	ds_read_b128 v[188:191], v243 offset:12288
	s_waitcnt lgkmcnt(3)
	v_mfma_f32_16x16x32_bf16 v[164:167], v[192:195], v[12:15], v[164:167]
	v_add_f32_e32 v137, v235, v199
	v_add_f32_e32 v138, v237, v212
	v_mfma_f32_16x16x32_bf16 v[160:163], v[192:195], v[28:31], v[160:163]
	v_cvt_pk_bf16_f32 v136, v152, v153
	v_add_u32_e32 v199, s49, v230
	ds_read_b128 v[192:195], v199
	v_add_f32_e32 v139, v236, v137
	v_add_f32_e32 v138, v238, v138
	s_waitcnt lgkmcnt(3)
	v_mfma_f32_16x16x32_bf16 v[132:135], v[180:183], v[12:15], v[132:135]
	v_cvt_pk_bf16_f32 v137, v154, v155
	v_mfma_f32_16x16x32_bf16 v[152:155], v[180:183], v[28:31], v[172:175]
	s_nop 2
	ds_read_b128 v[172:175], v199 offset:4096
	s_waitcnt lgkmcnt(3)
	v_mfma_f32_16x16x32_bf16 v[176:179], v[184:187], v[12:15], v[176:179]
	v_add_f32_e32 v139, v241, v139
	v_add_f32_e32 v212, v239, v138
	v_mfma_f32_16x16x32_bf16 v[140:143], v[184:187], v[28:31], v[140:143]
	v_cvt_pk_bf16_f32 v138, v156, v157
	ds_read_b128 v[180:183], v199 offset:8192
	v_add_f32_e32 v213, v242, v139
	v_add_f32_e32 v212, v240, v212
	s_waitcnt lgkmcnt(3)
	v_mfma_f32_16x16x32_bf16 v[128:131], v[188:191], v[12:15], v[128:131]
	v_cvt_pk_bf16_f32 v139, v158, v159
	v_mfma_f32_16x16x32_bf16 v[156:159], v[188:191], v[28:31], v[168:171]
	s_nop 2
	ds_read_b128 v[168:171], v199 offset:12288
	s_waitcnt lgkmcnt(3)
	v_mfma_f32_16x16x32_bf16 v[164:167], v[192:195], v[8:11], v[164:167]
	v_mfma_f32_16x16x32_bf16 v[184:187], v[192:195], v[24:27], v[160:163]
	s_nop 2
	v_add_f32_e32 v161, v210, v213
	v_add_f32_e32 v162, v215, v212
	v_cvt_pk_bf16_f32 v160, v144, v145
	v_add_u32_e32 v192, s49, v226
	ds_read_b128 v[188:191], v192 offset:16384
	v_add_f32_e32 v163, v211, v161
	v_add_f32_e32 v162, v214, v162
	s_waitcnt lgkmcnt(3)
	v_mfma_f32_16x16x32_bf16 v[132:135], v[172:175], v[8:11], v[132:135]
	v_cvt_pk_bf16_f32 v161, v146, v147
	v_mfma_f32_16x16x32_bf16 v[144:147], v[172:175], v[24:27], v[152:155]
	s_nop 2
	ds_read_b128 v[152:155], v192 offset:18432
	s_waitcnt lgkmcnt(3)
	v_mfma_f32_16x16x32_bf16 v[172:175], v[180:183], v[8:11], v[176:179]
	v_add_f32_e32 v163, v250, v163
	v_add_f32_e32 v193, v218, v162
	v_mfma_f32_16x16x32_bf16 v[140:143], v[180:183], v[24:27], v[140:143]
	v_cvt_pk_bf16_f32 v162, v148, v149
	ds_read_b128 v[176:179], v192 offset:20480
	v_add_f32_e32 v194, v251, v163
	v_add_f32_e32 v195, v198, v193
	s_waitcnt lgkmcnt(3)
	v_mfma_f32_16x16x32_bf16 v[128:131], v[168:171], v[8:11], v[128:131]
	v_cvt_pk_bf16_f32 v163, v150, v151
	v_mfma_f32_16x16x32_bf16 v[148:151], v[168:171], v[24:27], v[156:159]
	s_nop 2
	ds_read_b128 v[156:159], v192 offset:22528
	s_waitcnt lgkmcnt(3)
	v_mfma_f32_16x16x32_bf16 v[168:171], v[188:191], v[16:19], v[164:167]
	v_cvt_pk_bf16_f32 v164, v235, v236
	v_mfma_f32_16x16x32_bf16 v[180:183], v[188:191], v[32:35], v[184:187]
	v_add_u32_e32 v192, s49, v224
	s_nop 1
	ds_read_b128 v[184:187], v192 offset:16384
	s_waitcnt lgkmcnt(3)
	v_mfma_f32_16x16x32_bf16 v[132:135], v[152:155], v[16:19], v[132:135]
	v_cvt_pk_bf16_f32 v165, v241, v242
	v_mfma_f32_16x16x32_bf16 v[188:191], v[152:155], v[32:35], v[144:147]
	ds_read_b128 v[242:245], v192 offset:18432
	s_waitcnt lgkmcnt(3)
	v_mfma_f32_16x16x32_bf16 v[140:143], v[176:179], v[32:35], v[140:143]
	v_cvt_pk_bf16_f32 v166, v210, v211
	v_mfma_f32_16x16x32_bf16 v[246:249], v[176:179], v[16:19], v[172:175]
	ds_read_b128 v[176:179], v192 offset:20480
	s_waitcnt lgkmcnt(3)
	v_mfma_f32_16x16x32_bf16 v[128:131], v[156:159], v[16:19], v[128:131]
	v_cvt_pk_bf16_f32 v167, v250, v251
	v_mfma_f32_16x16x32_bf16 v[250:253], v[156:159], v[32:35], v[148:151]
	ds_read_b128 v[210:213], v192 offset:22528
	s_waitcnt lgkmcnt(3)
	v_mfma_f32_16x16x32_bf16 v[156:159], v[184:187], v[20:23], v[168:171]
	v_cvt_pk_bf16_f32 v168, v237, v238
	v_mfma_f32_16x16x32_bf16 v[144:147], v[184:187], v[44:47], v[180:183]
	s_waitcnt lgkmcnt(2)
	v_mfma_f32_16x16x32_bf16 v[152:155], v[242:245], v[20:23], v[132:135]
	v_cvt_pk_bf16_f32 v169, v239, v240
	v_mfma_f32_16x16x32_bf16 v[172:175], v[242:245], v[44:47], v[188:191]
	s_waitcnt lgkmcnt(1)
	v_mfma_f32_16x16x32_bf16 v[148:151], v[176:179], v[20:23], v[246:249]
	v_cvt_pk_bf16_f32 v170, v215, v214
	v_mfma_f32_16x16x32_bf16 v[140:143], v[176:179], v[44:47], v[140:143]
	s_waitcnt lgkmcnt(0)
	v_mfma_f32_16x16x32_bf16 v[132:135], v[210:213], v[20:23], v[128:131]
	v_cvt_pk_bf16_f32 v171, v218, v198
	v_mfma_f32_16x16x32_bf16 v[128:131], v[210:213], v[44:47], v[250:253]
	s_lshl_b32 s25, s5, 14
	s_add_i32 s25, s25, 0
	s_add_i32 s25, s25, 0x12000
	v_add_u32_e32 v235, s25, v222
	v_add_u32_e32 v236, s25, v223
	ds_read_b64_tr_b16 v[184:185], v236
	ds_read_b64_tr_b16 v[186:187], v236 offset:4096
	ds_read_b64_tr_b16 v[210:211], v236 offset:8192
	ds_read_b64_tr_b16 v[212:213], v236 offset:12288
	ds_read_b64_tr_b16 v[176:177], v235
	ds_read_b64_tr_b16 v[178:179], v235 offset:4096
	ds_read_b64_tr_b16 v[180:181], v235 offset:8192
	ds_read_b64_tr_b16 v[182:183], v235 offset:12288
	ds_read_b64_tr_b16 v[190:191], v236 offset:4608
	ds_read_b64_tr_b16 v[188:189], v236 offset:512
	ds_read_b64_tr_b16 v[240:241], v236 offset:12800
	ds_read_b64_tr_b16 v[238:239], v236 offset:8704
	s_waitcnt lgkmcnt(10)
	v_mfma_f32_16x16x32_bf16 v[112:115], v[184:187], v[136:139], v[112:115]
	v_mfma_f32_16x16x32_bf16 v[116:119], v[184:187], v[160:163], v[116:119]
	v_max_f32_e32 v184, v156, v157
	s_waitcnt lgkmcnt(8)
	v_mfma_f32_16x16x32_bf16 v[112:115], v[210:213], v[164:167], v[112:115]
	v_max3_f32 v184, v184, v158, v159
	v_max3_f32 v184, v184, v152, v153
	v_max3_f32 v184, v184, v154, v155
	v_mfma_f32_16x16x32_bf16 v[116:119], v[210:213], v[168:171], v[116:119]
	ds_read_b64_tr_b16 v[210:211], v235 offset:512
	ds_read_b64_tr_b16 v[212:213], v235 offset:4608
	ds_read_b64_tr_b16 v[242:243], v235 offset:8704
	ds_read_b64_tr_b16 v[244:245], v235 offset:12800
	s_waitcnt lgkmcnt(10)
	v_mfma_f32_16x16x32_bf16 v[104:107], v[176:179], v[136:139], v[104:107]
	v_mfma_f32_16x16x32_bf16 v[176:179], v[176:179], v[160:163], v[108:111]
	s_waitcnt lgkmcnt(8)
	v_mfma_f32_16x16x32_bf16 v[108:111], v[180:183], v[164:167], v[104:107]
	s_nop 5
	v_max3_f32 v104, v184, v148, v149
	v_max3_f32 v104, v104, v150, v151
	v_max3_f32 v104, v104, v132, v133
	v_max3_f32 v193, v104, v134, v135
	v_mfma_f32_16x16x32_bf16 v[104:107], v[180:183], v[168:171], v[176:179]
	ds_read_b64_tr_b16 v[184:185], v236 offset:1024
	ds_read_b64_tr_b16 v[186:187], v236 offset:5120
	s_nop 0
	ds_read_b64_tr_b16 v[176:177], v236 offset:9216
	ds_read_b64_tr_b16 v[178:179], v236 offset:13312
	s_waitcnt lgkmcnt(10)
	v_mfma_f32_16x16x32_bf16 v[96:99], v[188:191], v[136:139], v[96:99]
	v_max_f32_e32 v180, v144, v145
	s_waitcnt lgkmcnt(8)
	v_mfma_f32_16x16x32_bf16 v[96:99], v[238:241], v[164:167], v[96:99]
	v_max3_f32 v180, v180, v146, v147
	v_max3_f32 v180, v180, v172, v173
	v_max3_f32 v192, v180, v174, v175
	v_mfma_f32_16x16x32_bf16 v[100:103], v[188:191], v[160:163], v[100:103]
	v_mfma_f32_16x16x32_bf16 v[100:103], v[238:241], v[168:171], v[100:103]
	ds_read_b64_tr_b16 v[188:189], v235 offset:1024
	ds_read_b64_tr_b16 v[190:191], v235 offset:5120
	ds_read_b64_tr_b16 v[180:181], v235 offset:9216
	ds_read_b64_tr_b16 v[182:183], v235 offset:13312
	s_waitcnt lgkmcnt(10)
	v_mfma_f32_16x16x32_bf16 v[88:91], v[210:213], v[136:139], v[88:91]
	v_mfma_f32_16x16x32_bf16 v[210:213], v[210:213], v[160:163], v[92:95]
	s_waitcnt lgkmcnt(8)
	v_mfma_f32_16x16x32_bf16 v[92:95], v[242:245], v[164:167], v[88:91]
	s_nop 5
	v_max3_f32 v88, v192, v140, v141
	v_max3_f32 v88, v88, v142, v143
	v_max3_f32 v88, v88, v128, v129
	v_max3_f32 v237, v88, v130, v131
	v_mfma_f32_16x16x32_bf16 v[88:91], v[242:245], v[168:171], v[210:213]
	v_max_f32_e32 v192, v193, v237
	v_cmp_ge_f32_e32 vcc, s62, v192
	s_cmp_lg_u64 vcc, exec
	s_cselect_b64 s[36:37], -1, 0
	s_cmp_eq_u64 vcc, exec
	v_mov_b32_e32 v192, 1.0
	s_cbranch_scc1 .LBB0_973
	ds_bpermute_b32 v48, v220, v193
	v_max_f32_e32 v49, v193, v193
	v_max_f32_e32 v50, v237, v237
	s_waitcnt lgkmcnt(0)
	v_max_f32_e32 v48, v48, v48
	v_max_f32_e32 v48, v49, v48
	ds_bpermute_b32 v49, v221, v48
	s_waitcnt lgkmcnt(0)
	v_max3_f32 v48, v48, v49, 0
	ds_bpermute_b32 v49, v220, v237
	v_exp_f32_e64 v192, -v48
	v_sub_f32_e32 v156, v156, v48
	v_sub_f32_e32 v157, v157, v48
	v_sub_f32_e32 v158, v158, v48
	s_waitcnt lgkmcnt(0)
	v_max_f32_e32 v49, v49, v49
	v_max_f32_e32 v49, v50, v49
	ds_bpermute_b32 v50, v221, v49
	v_sub_f32_e32 v159, v159, v48
	v_sub_f32_e32 v152, v152, v48
	v_sub_f32_e32 v153, v153, v48
	v_sub_f32_e32 v154, v154, v48
	s_waitcnt lgkmcnt(0)
	v_max3_f32 v49, v49, v50, 0
	v_exp_f32_e64 v193, -v49
	v_pk_add_f32 v[202:203], v[202:203], v[48:49]
	v_sub_f32_e32 v155, v155, v48
	v_pk_add_f32 v[120:121], v[202:203], 0 neg_lo:[1,1] neg_hi:[1,1]
	v_xor_b32_e32 v124, 0x80000000, v203
	v_sub_f32_e32 v151, v151, v48
	v_sub_f32_e32 v150, v150, v48
	v_sub_f32_e32 v149, v149, v48
	v_sub_f32_e32 v148, v148, v48
	v_sub_f32_e32 v135, v135, v48
	v_sub_f32_e32 v134, v134, v48
	v_sub_f32_e32 v133, v133, v48
	v_sub_f32_e32 v132, v132, v48
	v_mov_b32_e32 v121, v120
	v_mov_b32_e32 v122, v120
	v_mov_b32_e32 v123, v120
	v_sub_f32_e32 v144, v144, v49
	v_sub_f32_e32 v145, v145, v49
	v_sub_f32_e32 v146, v146, v49
	v_sub_f32_e32 v147, v147, v49
	v_sub_f32_e32 v172, v172, v49
	v_sub_f32_e32 v173, v173, v49
	v_sub_f32_e32 v174, v174, v49
	v_sub_f32_e32 v175, v175, v49
	v_sub_f32_e32 v143, v143, v49
	v_sub_f32_e32 v142, v142, v49
	v_sub_f32_e32 v141, v141, v49
	v_sub_f32_e32 v140, v140, v49
	v_sub_f32_e32 v131, v131, v49
	v_sub_f32_e32 v130, v130, v49
	v_sub_f32_e32 v129, v129, v49
	v_sub_f32_e32 v128, v128, v49
	v_mov_b32_e32 v125, v124
	v_mov_b32_e32 v126, v124
	v_mov_b32_e32 v127, v124
	v_mov_b32_e32 v48, v120
	v_mov_b32_e32 v49, v120
	v_mov_b32_e32 v50, v120
	v_mov_b32_e32 v51, v120
	v_mov_b32_e32 v52, v124
	v_mov_b32_e32 v53, v124
	v_mov_b32_e32 v54, v124
	v_mov_b32_e32 v55, v124
	s_branch .LBB0_974
